# vres block operand loads in the fast 4-rows-x-64-B-per-quarter pattern (permuted back through LDS); plus rstd_table full-line loads, epilogue load transform, PRM overlap
# speedup vs baseline: 1.0003x; 1.0003x over previous
; #define GAS __attribute__((address_space(1)))
; #define LAS __attribute__((address_space(3)))
;     DI void init(const bf16* A_, int lda, const bf16* B_, int ldb, int nM, int nN, int K, int G_, int c_) { T.init(nM, nN); G = G_; c = c_; nt = K / BK; A = (const char*)A_; B = (const char*)B_; ta = (size_t)BM * lda * 2; tb = (size_t)BM * ldb * 2; }
;     DI void init(const bf16* A_, int lda, const bf16* B_, int ldb, int nM, int nN, int G_, int c_) { T.init(nM, nN); G = G_; c = c_; A = (const char*)A_; B = (const char*)B_; ta = (size_t)BM * lda * 2; tb = (size_t)BM * ldb * 2; }
; #define SB() __builtin_amdgcn_sched_barrier(0)
; #define FRAME() const CAS Args* ap; const Frame F = make_frame(lds, ap, wv); const CAS Args& A = *ap; (void)A
; DI const LAS float* rstd_table(const Frame& F) {
;     ...
;     for (int r = F.tid; r < 2048; r += 512) { f32x4 p[8];
; #pragma unroll
;         for (int q = 0; q < 8; ++q) p[q] = ((const GAS f32x4*)(P + (size_t)r * 32))[q];
;         SB();
;         f32x4 t = (p[0] + p[1]) + (p[2] + p[3]) + ((p[4] + p[5]) + (p[6] + p[7]));
;         tab[r] = 1.f / sqrtf(((t[0] + t[1]) + (t[2] + t[3])) * (1.f / D) + NORM_EPS);
; __global__ void __launch_bounds__(512, 2) trunk_fwd(Args args_unused) {
;     ...
;         if (PHEN(1) && IN(s0 + 1)) { FRAME();
;             const int nN = (l == 0) ? 44 : 45;
;             const LAS float* rs = rstd_table(F);
;             SchedPlain S; S.init((const bf16*)F.out, XP, (const bf16*)lw(F, l, LW_WIN), D, M / BM, nN, D, F.G, F.bid);
;             EpiInproj E{(bf16*)(F.ws + WS_R2), A.in[3] + (size_t)l * 6144, (bf16*)(F.ws + WS_ZS5), rs};
;             gemm_phase<EpiInproj, SchedPlain>(F.lds, F.wave, XP, D, S, E);
.Lvres_chunk:
	s_mov_b32 s0, m0
	v_and_b32_e32 v239, 15, v238
	v_lshrrev_b32_e32 v240, 4, v238
	s_lshl_b32 s0, s0, 6
	s_and_b32 s1, s90, 3
	s_lshl_b32 s1, s1, 4
	s_add_i32 s1, s0, s1
	v_add_u32_e32 v184, s1, v239
	v_lshlrev_b32_e32 v241, 7, v184
	v_mul_u32_u24_e32 v242, 0x5a00, v184
	v_lshl_add_u32 v242, v240, 3, v242
	v_add_u32_e32 v243, s0, v239
	v_lshlrev_b32_e32 v243, 12, v243
	v_lshl_add_u32 v243, v240, 4, v243
	s_lshl_b32 s2, s90, 9
	v_add_u32_e32 v243, s2, v243
	v_add_u32_e32 v244, 0x10000, v243
	v_add_u32_e32 v245, 0x20000, v243
	v_add_u32_e32 v246, 0x30000, v243
	v_lshlrev_b32_e32 v247, 12, v239
	v_lshl_add_u32 v247, v240, 4, v247
	v_add_u32_e32 v247, s2, v247
	v_add_u32_e32 v248, 0x10000, v247
	v_add_u32_e32 v249, 0x20000, v247
	s_mul_i32 s17, s71, 0x7eca000
	s_waitcnt lgkmcnt(0)
	s_add_u32 s100, s6, 0x49c28000
	s_addc_u32 s101, s7, 0
	global_load_dwordx4 v[196:199], v241, s[100:101] offset:32
	global_load_dwordx4 v[200:203], v241, s[100:101] offset:48
	global_load_dwordx4 v[204:207], v241, s[100:101]
	global_load_dwordx4 v[208:211], v241, s[100:101] offset:16
	global_load_dwordx4 v[212:215], v241, s[100:101] offset:96
	global_load_dwordx4 v[216:219], v241, s[100:101] offset:112
	global_load_dwordx4 v[220:223], v241, s[100:101] offset:64
	global_load_dwordx4 v[234:237], v241, s[100:101] offset:80
	v_bfe_u32 v0, v238, 2, 2
	v_lshl_add_u32 v0, v240, 2, v0
	v_sub_u32_e32 v0, v0, v239
	v_and_b32_e32 v1, 3, v238
	v_sub_u32_e32 v1, v1, v240
	v_lshlrev_b32_e32 v1, 4, v1
	v_lshl_add_u32 v0, v0, 12, v1
	v_add_u32_e32 v243, v243, v0
	v_add_u32_e32 v244, v244, v0
	v_add_u32_e32 v245, v245, v0
	v_add_u32_e32 v246, v246, v0
	v_add_u32_e32 v247, v247, v0
	v_add_u32_e32 v248, v248, v0
	v_add_u32_e32 v249, v249, v0
	s_lshl_b32 s2, s90, 10
	s_add_i32 s2, s2, 0x22000
	v_lshl_add_u32 v241, v238, 4, s2
	v_lshrrev_b32_e32 v1, 2, v239
	v_lshl_add_u32 v1, v1, 4, v240
	v_and_b32_e32 v2, 3, v239
	v_lshl_add_u32 v1, v2, 2, v1
	v_lshl_add_u32 v186, v1, 4, s2
	s_add_u32 s0, s6, s17
	s_addc_u32 s1, s7, 0
	s_add_u32 s0, s0, 0x2d00000
	s_addc_u32 s1, s1, 0
	s_add_u32 s16, s6, 0x23c2d800
	s_addc_u32 s17, s7, 0
	global_load_dwordx4 v[0:3], v243, s[4:5]
	global_load_dwordx4 v[4:7], v244, s[4:5]
	global_load_dwordx4 v[8:11], v245, s[4:5]
	global_load_dwordx4 v[12:15], v246, s[4:5]
	global_load_dwordx4 v[16:19], v247, s[0:1]
	global_load_dwordx4 v[20:23], v248, s[0:1]
	global_load_dwordx4 v[24:27], v249, s[0:1]
	global_load_dwordx4 v[28:31], v243, s[4:5] offset:64
	global_load_dwordx4 v[32:35], v244, s[4:5] offset:64
	global_load_dwordx4 v[36:39], v245, s[4:5] offset:64
	global_load_dwordx4 v[40:43], v246, s[4:5] offset:64
	global_load_dwordx4 v[44:47], v247, s[0:1] offset:64
	global_load_dwordx4 v[48:51], v248, s[0:1] offset:64
	global_load_dwordx4 v[52:55], v249, s[0:1] offset:64
	global_load_dwordx4 v[56:59], v243, s[4:5] offset:128
	global_load_dwordx4 v[60:63], v244, s[4:5] offset:128
	global_load_dwordx4 v[64:67], v245, s[4:5] offset:128
	global_load_dwordx4 v[68:71], v246, s[4:5] offset:128
	global_load_dwordx4 v[72:75], v247, s[0:1] offset:128
	global_load_dwordx4 v[76:79], v248, s[0:1] offset:128
	global_load_dwordx4 v[80:83], v249, s[0:1] offset:128
	global_load_dwordx4 v[84:87], v243, s[4:5] offset:192
	global_load_dwordx4 v[88:91], v244, s[4:5] offset:192
	global_load_dwordx4 v[92:95], v245, s[4:5] offset:192
	global_load_dwordx4 v[96:99], v246, s[4:5] offset:192
	global_load_dwordx4 v[100:103], v247, s[0:1] offset:192
	global_load_dwordx4 v[104:107], v248, s[0:1] offset:192
	global_load_dwordx4 v[108:111], v249, s[0:1] offset:192
	global_load_dwordx4 v[112:115], v243, s[4:5] offset:256
	global_load_dwordx4 v[116:119], v244, s[4:5] offset:256
	global_load_dwordx4 v[120:123], v245, s[4:5] offset:256
	global_load_dwordx4 v[124:127], v246, s[4:5] offset:256
	global_load_dwordx4 v[128:131], v247, s[0:1] offset:256
	global_load_dwordx4 v[132:135], v248, s[0:1] offset:256
	global_load_dwordx4 v[136:139], v249, s[0:1] offset:256
	s_waitcnt vmcnt(28)
	ds_write_b128 v241, v[0:3]
	ds_read_b128 v[0:3], v186
	ds_write_b128 v241, v[4:7]
	ds_read_b128 v[4:7], v186
	ds_write_b128 v241, v[8:11]
	ds_read_b128 v[8:11], v186
	ds_write_b128 v241, v[12:15]
	ds_read_b128 v[12:15], v186
	ds_write_b128 v241, v[16:19]
	ds_read_b128 v[16:19], v186
	ds_write_b128 v241, v[20:23]
	ds_read_b128 v[20:23], v186
	ds_write_b128 v241, v[24:27]
	ds_read_b128 v[24:27], v186
	s_waitcnt lgkmcnt(0)
	v_mfma_f32_16x16x32_bf16 v[140:143], v[16:19], v[0:3], 0
	v_mfma_f32_16x16x32_bf16 v[144:147], v[20:23], v[0:3], 0
	v_mfma_f32_16x16x32_bf16 v[148:151], v[24:27], v[0:3], 0
	v_mfma_f32_16x16x32_bf16 v[152:155], v[16:19], v[4:7], 0
	v_mfma_f32_16x16x32_bf16 v[156:159], v[20:23], v[4:7], 0
	v_mfma_f32_16x16x32_bf16 v[160:163], v[24:27], v[4:7], 0
	v_mfma_f32_16x16x32_bf16 v[164:167], v[16:19], v[8:11], 0
	v_mfma_f32_16x16x32_bf16 v[168:171], v[20:23], v[8:11], 0
	v_mfma_f32_16x16x32_bf16 v[172:175], v[24:27], v[8:11], 0
	v_mfma_f32_16x16x32_bf16 v[176:179], v[16:19], v[12:15], 0
	v_mfma_f32_16x16x32_bf16 v[180:183], v[20:23], v[12:15], 0
	v_mfma_f32_16x16x32_bf16 v[188:191], v[24:27], v[12:15], 0
	global_load_dwordx4 v[0:3], v243, s[4:5] offset:320
	global_load_dwordx4 v[4:7], v244, s[4:5] offset:320
	global_load_dwordx4 v[8:11], v245, s[4:5] offset:320
	global_load_dwordx4 v[12:15], v246, s[4:5] offset:320
	global_load_dwordx4 v[16:19], v247, s[0:1] offset:320
	global_load_dwordx4 v[20:23], v248, s[0:1] offset:320
	global_load_dwordx4 v[24:27], v249, s[0:1] offset:320
	s_waitcnt vmcnt(28)
; #define LAS __attribute__((address_space(3)))
;     DI void init(const bf16* A_, int lda, const bf16* B_, int ldb, int nM, int nN, int K, int G_, int c_) { T.init(nM, nN); G = G_; c = c_; nt = K / BK; A = (const char*)A_; B = (const char*)B_; ta = (size_t)BM * lda * 2; tb = (size_t)BM * ldb * 2; }
;     DI void init(const bf16* A_, int lda, const bf16* B_, int ldb, int nM, int nN, int G_, int c_) { T.init(nM, nN); G = G_; c = c_; A = (const char*)A_; B = (const char*)B_; ta = (size_t)BM * lda * 2; tb = (size_t)BM * ldb * 2; }
; #define FRAME() const CAS Args* ap; const Frame F = make_frame(lds, ap, wv); const CAS Args& A = *ap; (void)A
; __global__ void __launch_bounds__(512, 2) trunk_fwd(Args args_unused) {
;     ...
;         if (PHEN(1) && IN(s0 + 1)) { FRAME();
;             const int nN = (l == 0) ? 44 : 45;
;             const LAS float* rs = rstd_table(F);
;             SchedPlain S; S.init((const bf16*)F.out, XP, (const bf16*)lw(F, l, LW_WIN), D, M / BM, nN, D, F.G, F.bid);
;             EpiInproj E{(bf16*)(F.ws + WS_R2), A.in[3] + (size_t)l * 6144, (bf16*)(F.ws + WS_ZS5), rs};
;             gemm_phase<EpiInproj, SchedPlain>(F.lds, F.wave, XP, D, S, E);
	ds_write_b128 v241, v[28:31]
	ds_read_b128 v[28:31], v186
	ds_write_b128 v241, v[32:35]
	ds_read_b128 v[32:35], v186
	ds_write_b128 v241, v[36:39]
	ds_read_b128 v[36:39], v186
	ds_write_b128 v241, v[40:43]
	ds_read_b128 v[40:43], v186
	ds_write_b128 v241, v[44:47]
	ds_read_b128 v[44:47], v186
	ds_write_b128 v241, v[48:51]
	ds_read_b128 v[48:51], v186
	ds_write_b128 v241, v[52:55]
	ds_read_b128 v[52:55], v186
	s_waitcnt lgkmcnt(0)
	v_mfma_f32_16x16x32_bf16 v[140:143], v[44:47], v[28:31], v[140:143]
	v_mfma_f32_16x16x32_bf16 v[144:147], v[48:51], v[28:31], v[144:147]
	v_mfma_f32_16x16x32_bf16 v[148:151], v[52:55], v[28:31], v[148:151]
	v_mfma_f32_16x16x32_bf16 v[152:155], v[44:47], v[32:35], v[152:155]
	v_mfma_f32_16x16x32_bf16 v[156:159], v[48:51], v[32:35], v[156:159]
	v_mfma_f32_16x16x32_bf16 v[160:163], v[52:55], v[32:35], v[160:163]
	v_mfma_f32_16x16x32_bf16 v[164:167], v[44:47], v[36:39], v[164:167]
	v_mfma_f32_16x16x32_bf16 v[168:171], v[48:51], v[36:39], v[168:171]
	v_mfma_f32_16x16x32_bf16 v[172:175], v[52:55], v[36:39], v[172:175]
	v_mfma_f32_16x16x32_bf16 v[176:179], v[44:47], v[40:43], v[176:179]
	v_mfma_f32_16x16x32_bf16 v[180:183], v[48:51], v[40:43], v[180:183]
	v_mfma_f32_16x16x32_bf16 v[188:191], v[52:55], v[40:43], v[188:191]
	global_load_dwordx4 v[28:31], v243, s[4:5] offset:384
	global_load_dwordx4 v[32:35], v244, s[4:5] offset:384
	global_load_dwordx4 v[36:39], v245, s[4:5] offset:384
	global_load_dwordx4 v[40:43], v246, s[4:5] offset:384
	global_load_dwordx4 v[44:47], v247, s[0:1] offset:384
	global_load_dwordx4 v[48:51], v248, s[0:1] offset:384
	global_load_dwordx4 v[52:55], v249, s[0:1] offset:384
	s_waitcnt vmcnt(28)
	ds_write_b128 v241, v[56:59]
	ds_read_b128 v[56:59], v186
	ds_write_b128 v241, v[60:63]
	ds_read_b128 v[60:63], v186
	ds_write_b128 v241, v[64:67]
	ds_read_b128 v[64:67], v186
	ds_write_b128 v241, v[68:71]
	ds_read_b128 v[68:71], v186
	ds_write_b128 v241, v[72:75]
	ds_read_b128 v[72:75], v186
	ds_write_b128 v241, v[76:79]
	ds_read_b128 v[76:79], v186
	ds_write_b128 v241, v[80:83]
	ds_read_b128 v[80:83], v186
	s_waitcnt lgkmcnt(0)
	v_mfma_f32_16x16x32_bf16 v[140:143], v[72:75], v[56:59], v[140:143]
	v_mfma_f32_16x16x32_bf16 v[144:147], v[76:79], v[56:59], v[144:147]
	v_mfma_f32_16x16x32_bf16 v[148:151], v[80:83], v[56:59], v[148:151]
	v_mfma_f32_16x16x32_bf16 v[152:155], v[72:75], v[60:63], v[152:155]
	v_mfma_f32_16x16x32_bf16 v[156:159], v[76:79], v[60:63], v[156:159]
	v_mfma_f32_16x16x32_bf16 v[160:163], v[80:83], v[60:63], v[160:163]
	v_mfma_f32_16x16x32_bf16 v[164:167], v[72:75], v[64:67], v[164:167]
	v_mfma_f32_16x16x32_bf16 v[168:171], v[76:79], v[64:67], v[168:171]
	v_mfma_f32_16x16x32_bf16 v[172:175], v[80:83], v[64:67], v[172:175]
	v_mfma_f32_16x16x32_bf16 v[176:179], v[72:75], v[68:71], v[176:179]
	v_mfma_f32_16x16x32_bf16 v[180:183], v[76:79], v[68:71], v[180:183]
	v_mfma_f32_16x16x32_bf16 v[188:191], v[80:83], v[68:71], v[188:191]
	global_load_dwordx4 v[56:59], v243, s[4:5] offset:448
	global_load_dwordx4 v[60:63], v244, s[4:5] offset:448
	global_load_dwordx4 v[64:67], v245, s[4:5] offset:448
	global_load_dwordx4 v[68:71], v246, s[4:5] offset:448
	global_load_dwordx4 v[72:75], v247, s[0:1] offset:448
	global_load_dwordx4 v[76:79], v248, s[0:1] offset:448
	global_load_dwordx4 v[80:83], v249, s[0:1] offset:448
	s_waitcnt vmcnt(28)
	ds_write_b128 v241, v[84:87]
	ds_read_b128 v[84:87], v186
	ds_write_b128 v241, v[88:91]
	ds_read_b128 v[88:91], v186
	ds_write_b128 v241, v[92:95]
	ds_read_b128 v[92:95], v186
	ds_write_b128 v241, v[96:99]
	ds_read_b128 v[96:99], v186
	ds_write_b128 v241, v[100:103]
	ds_read_b128 v[100:103], v186
	ds_write_b128 v241, v[104:107]
	ds_read_b128 v[104:107], v186
	ds_write_b128 v241, v[108:111]
	ds_read_b128 v[108:111], v186
	s_waitcnt lgkmcnt(0)
	v_mfma_f32_16x16x32_bf16 v[140:143], v[100:103], v[84:87], v[140:143]
	v_mfma_f32_16x16x32_bf16 v[144:147], v[104:107], v[84:87], v[144:147]
	v_mfma_f32_16x16x32_bf16 v[148:151], v[108:111], v[84:87], v[148:151]
	v_mfma_f32_16x16x32_bf16 v[152:155], v[100:103], v[88:91], v[152:155]
	v_mfma_f32_16x16x32_bf16 v[156:159], v[104:107], v[88:91], v[156:159]
	v_mfma_f32_16x16x32_bf16 v[160:163], v[108:111], v[88:91], v[160:163]
	v_mfma_f32_16x16x32_bf16 v[164:167], v[100:103], v[92:95], v[164:167]
	v_mfma_f32_16x16x32_bf16 v[168:171], v[104:107], v[92:95], v[168:171]
	v_mfma_f32_16x16x32_bf16 v[172:175], v[108:111], v[92:95], v[172:175]
	v_mfma_f32_16x16x32_bf16 v[176:179], v[100:103], v[96:99], v[176:179]
	v_mfma_f32_16x16x32_bf16 v[180:183], v[104:107], v[96:99], v[180:183]
	v_mfma_f32_16x16x32_bf16 v[188:191], v[108:111], v[96:99], v[188:191]
	s_waitcnt vmcnt(21)
	ds_write_b128 v241, v[112:115]
	ds_read_b128 v[112:115], v186
	ds_write_b128 v241, v[116:119]
	ds_read_b128 v[116:119], v186
	ds_write_b128 v241, v[120:123]
	ds_read_b128 v[120:123], v186
	ds_write_b128 v241, v[124:127]
	ds_read_b128 v[124:127], v186
	ds_write_b128 v241, v[128:131]
	ds_read_b128 v[128:131], v186
	ds_write_b128 v241, v[132:135]
	ds_read_b128 v[132:135], v186
	ds_write_b128 v241, v[136:139]
	ds_read_b128 v[136:139], v186
	s_waitcnt lgkmcnt(0)
	v_mfma_f32_16x16x32_bf16 v[140:143], v[128:131], v[112:115], v[140:143]
	v_mfma_f32_16x16x32_bf16 v[144:147], v[132:135], v[112:115], v[144:147]
	v_mfma_f32_16x16x32_bf16 v[148:151], v[136:139], v[112:115], v[148:151]
	v_mfma_f32_16x16x32_bf16 v[152:155], v[128:131], v[116:119], v[152:155]
	v_mfma_f32_16x16x32_bf16 v[156:159], v[132:135], v[116:119], v[156:159]
	v_mfma_f32_16x16x32_bf16 v[160:163], v[136:139], v[116:119], v[160:163]
	v_mfma_f32_16x16x32_bf16 v[164:167], v[128:131], v[120:123], v[164:167]
	v_mfma_f32_16x16x32_bf16 v[168:171], v[132:135], v[120:123], v[168:171]
	v_mfma_f32_16x16x32_bf16 v[172:175], v[136:139], v[120:123], v[172:175]
	v_mfma_f32_16x16x32_bf16 v[176:179], v[128:131], v[124:127], v[176:179]
	v_mfma_f32_16x16x32_bf16 v[180:183], v[132:135], v[124:127], v[180:183]
	v_mfma_f32_16x16x32_bf16 v[188:191], v[136:139], v[124:127], v[188:191]
	s_waitcnt vmcnt(14)
; #define LAS __attribute__((address_space(3)))
;     DI void init(const bf16* A_, int lda, const bf16* B_, int ldb, int nM, int nN, int K, int G_, int c_) { T.init(nM, nN); G = G_; c = c_; nt = K / BK; A = (const char*)A_; B = (const char*)B_; ta = (size_t)BM * lda * 2; tb = (size_t)BM * ldb * 2; }
;     DI void init(const bf16* A_, int lda, const bf16* B_, int ldb, int nM, int nN, int G_, int c_) { T.init(nM, nN); G = G_; c = c_; A = (const char*)A_; B = (const char*)B_; ta = (size_t)BM * lda * 2; tb = (size_t)BM * ldb * 2; }
; #define FRAME() const CAS Args* ap; const Frame F = make_frame(lds, ap, wv); const CAS Args& A = *ap; (void)A
; __global__ void __launch_bounds__(512, 2) trunk_fwd(Args args_unused) {
;     ...
;         if (PHEN(1) && IN(s0 + 1)) { FRAME();
;             const int nN = (l == 0) ? 44 : 45;
;             const LAS float* rs = rstd_table(F);
;             SchedPlain S; S.init((const bf16*)F.out, XP, (const bf16*)lw(F, l, LW_WIN), D, M / BM, nN, D, F.G, F.bid);
;             EpiInproj E{(bf16*)(F.ws + WS_R2), A.in[3] + (size_t)l * 6144, (bf16*)(F.ws + WS_ZS5), rs};
;             gemm_phase<EpiInproj, SchedPlain>(F.lds, F.wave, XP, D, S, E);
	ds_write_b128 v241, v[0:3]
	ds_read_b128 v[0:3], v186
	ds_write_b128 v241, v[4:7]
	ds_read_b128 v[4:7], v186
	ds_write_b128 v241, v[8:11]
	ds_read_b128 v[8:11], v186
	ds_write_b128 v241, v[12:15]
	ds_read_b128 v[12:15], v186
	ds_write_b128 v241, v[16:19]
	ds_read_b128 v[16:19], v186
	ds_write_b128 v241, v[20:23]
	ds_read_b128 v[20:23], v186
	ds_write_b128 v241, v[24:27]
	ds_read_b128 v[24:27], v186
	s_waitcnt lgkmcnt(0)
	v_mfma_f32_16x16x32_bf16 v[140:143], v[16:19], v[0:3], v[140:143]
	v_mfma_f32_16x16x32_bf16 v[144:147], v[20:23], v[0:3], v[144:147]
	v_mfma_f32_16x16x32_bf16 v[148:151], v[24:27], v[0:3], v[148:151]
	v_mfma_f32_16x16x32_bf16 v[152:155], v[16:19], v[4:7], v[152:155]
	v_mfma_f32_16x16x32_bf16 v[156:159], v[20:23], v[4:7], v[156:159]
	v_mfma_f32_16x16x32_bf16 v[160:163], v[24:27], v[4:7], v[160:163]
	v_mfma_f32_16x16x32_bf16 v[164:167], v[16:19], v[8:11], v[164:167]
	v_mfma_f32_16x16x32_bf16 v[168:171], v[20:23], v[8:11], v[168:171]
	v_mfma_f32_16x16x32_bf16 v[172:175], v[24:27], v[8:11], v[172:175]
	v_mfma_f32_16x16x32_bf16 v[176:179], v[16:19], v[12:15], v[176:179]
	v_mfma_f32_16x16x32_bf16 v[180:183], v[20:23], v[12:15], v[180:183]
	v_mfma_f32_16x16x32_bf16 v[188:191], v[24:27], v[12:15], v[188:191]
	s_waitcnt vmcnt(7)
	ds_write_b128 v241, v[28:31]
	ds_read_b128 v[28:31], v186
	ds_write_b128 v241, v[32:35]
	ds_read_b128 v[32:35], v186
	ds_write_b128 v241, v[36:39]
	ds_read_b128 v[36:39], v186
	ds_write_b128 v241, v[40:43]
	ds_read_b128 v[40:43], v186
	ds_write_b128 v241, v[44:47]
	ds_read_b128 v[44:47], v186
	ds_write_b128 v241, v[48:51]
	ds_read_b128 v[48:51], v186
	ds_write_b128 v241, v[52:55]
	ds_read_b128 v[52:55], v186
	s_waitcnt lgkmcnt(0)
	v_mfma_f32_16x16x32_bf16 v[140:143], v[44:47], v[28:31], v[140:143]
	v_mfma_f32_16x16x32_bf16 v[144:147], v[48:51], v[28:31], v[144:147]
	v_mfma_f32_16x16x32_bf16 v[148:151], v[52:55], v[28:31], v[148:151]
	v_mfma_f32_16x16x32_bf16 v[152:155], v[44:47], v[32:35], v[152:155]
	v_mfma_f32_16x16x32_bf16 v[156:159], v[48:51], v[32:35], v[156:159]
	v_mfma_f32_16x16x32_bf16 v[160:163], v[52:55], v[32:35], v[160:163]
	v_mfma_f32_16x16x32_bf16 v[164:167], v[44:47], v[36:39], v[164:167]
	v_mfma_f32_16x16x32_bf16 v[168:171], v[48:51], v[36:39], v[168:171]
	v_mfma_f32_16x16x32_bf16 v[172:175], v[52:55], v[36:39], v[172:175]
	v_mfma_f32_16x16x32_bf16 v[176:179], v[44:47], v[40:43], v[176:179]
	v_mfma_f32_16x16x32_bf16 v[180:183], v[48:51], v[40:43], v[180:183]
	v_mfma_f32_16x16x32_bf16 v[188:191], v[52:55], v[40:43], v[188:191]
	s_waitcnt vmcnt(0)
	ds_write_b128 v241, v[56:59]
	ds_read_b128 v[56:59], v186
	ds_write_b128 v241, v[60:63]
	ds_read_b128 v[60:63], v186
	ds_write_b128 v241, v[64:67]
	ds_read_b128 v[64:67], v186
	ds_write_b128 v241, v[68:71]
	ds_read_b128 v[68:71], v186
	ds_write_b128 v241, v[72:75]
	ds_read_b128 v[72:75], v186
	ds_write_b128 v241, v[76:79]
	ds_read_b128 v[76:79], v186
	ds_write_b128 v241, v[80:83]
	ds_read_b128 v[80:83], v186
	s_waitcnt lgkmcnt(0)
	v_mfma_f32_16x16x32_bf16 v[140:143], v[72:75], v[56:59], v[140:143]
	v_mfma_f32_16x16x32_bf16 v[144:147], v[76:79], v[56:59], v[144:147]
	v_mfma_f32_16x16x32_bf16 v[148:151], v[80:83], v[56:59], v[148:151]
	v_mfma_f32_16x16x32_bf16 v[152:155], v[72:75], v[60:63], v[152:155]
	v_mfma_f32_16x16x32_bf16 v[156:159], v[76:79], v[60:63], v[156:159]
	v_mfma_f32_16x16x32_bf16 v[160:163], v[80:83], v[60:63], v[160:163]
	v_mfma_f32_16x16x32_bf16 v[164:167], v[72:75], v[64:67], v[164:167]
	v_mfma_f32_16x16x32_bf16 v[168:171], v[76:79], v[64:67], v[168:171]
	v_mfma_f32_16x16x32_bf16 v[172:175], v[80:83], v[64:67], v[172:175]
	v_mfma_f32_16x16x32_bf16 v[176:179], v[72:75], v[68:71], v[176:179]
	v_mfma_f32_16x16x32_bf16 v[180:183], v[76:79], v[68:71], v[180:183]
	v_mfma_f32_16x16x32_bf16 v[188:191], v[80:83], v[68:71], v[188:191]
	v_lshlrev_b32_e32 v0, 4, v238
	s_lshl_b32 s2, s90, 10
	v_add_u32_e32 v1, s2, v0
	v_add_u32_e32 v2, 0xc000, v1
	s_nop 15
	s_nop 15
	ds_write_b128 v1, v[140:143]
	ds_write_b128 v1, v[144:147] offset:8192
	ds_write_b128 v1, v[148:151] offset:16384
	ds_write_b128 v1, v[152:155] offset:24576
	ds_write_b128 v1, v[156:159] offset:32768
	ds_write_b128 v1, v[160:163] offset:40960
	ds_write_b128 v2, v[164:167]
	ds_write_b128 v2, v[168:171] offset:8192
	ds_write_b128 v2, v[172:175] offset:16384
	ds_write_b128 v2, v[176:179] offset:24576
	ds_write_b128 v2, v[180:183] offset:32768
	ds_write_b128 v2, v[188:191] offset:40960
	s_waitcnt lgkmcnt(0)
	s_barrier
; #define GAS __attribute__((address_space(1)))
; DI unsigned pk2(float lo, float hi) { f32x2 v = {lo, hi}; bf16x2_t r = __builtin_convertvector(v, bf16x2_t); return __builtin_bit_cast(unsigned, r); }
; DI float sigmoidf_(float x) { return __builtin_amdgcn_rcpf(1.f + __expf(-x)); }
; #define SB() __builtin_amdgcn_sched_barrier(0)
;     DI bool operator()(AccT& acc, const Unit& u, int wr, int wc, int fr, int fq) const {
;     ...
;                     f32x4 v0 = acc[ai][bj][m][0] * rsv[ai][m], v1 = acc[ai][bj][m][1] * rsv[ai][m];
;                     if (gate) { v0 += b0; v1 += b1;
; #pragma unroll
;                         for (int e = 0; e < 4; ++e) { v0[e] = sigmoidf_(v0[e]); v1[e] = sigmoidf_(v1[e]); } }
;                     u32x4 w; w.x = pk2(v0[0], v0[1]); w.y = pk2(v0[2], v0[3]); w.z = pk2(v1[0], v1[1]); w.w = pk2(v1[2], v1[3]);
;                     if (s5c) *(GAS u32x4*)(ZS5 + ((size_t)(col >> 4) * M + (row0 + ai * HALF + m * 16)) * 16 + (col & 8)) = w;
;                     else *(GAS u32x4*)(Z + (size_t)(row0 + ai * HALF + m * 16) * ZP + col) = w;
; DI const LAS float* rstd_table(const Frame& F) {
;     ...
;     for (int r = F.tid; r < 2048; r += 512) { f32x4 p[8];
; #pragma unroll
;         for (int q = 0; q < 8; ++q) p[q] = ((const GAS f32x4*)(P + (size_t)r * 32))[q];
;         SB();
;         f32x4 t = (p[0] + p[1]) + (p[2] + p[3]) + ((p[4] + p[5]) + (p[6] + p[7]));
;         tab[r] = 1.f / sqrtf(((t[0] + t[1]) + (t[2] + t[3])) * (1.f / D) + NORM_EPS);
	s_and_b32 s2, s90, 3
	s_mul_i32 s2, s2, 3
	s_lshr_b32 s3, s90, 2
	s_add_i32 s98, s2, s3
	s_add_i32 s99, s2, 2
	s_lshl_b32 s98, s98, 13
	s_lshl_b32 s99, s99, 13
	v_add_u32_e32 v3, s98, v0
	v_add_u32_e32 v4, s99, v0
	ds_read_b128 v[8:11], v3
	ds_read_b128 v[12:15], v3 offset:1024
	ds_read_b128 v[16:19], v3 offset:2048
	ds_read_b128 v[20:23], v3 offset:3072
	ds_read_b128 v[24:27], v3 offset:4096
	ds_read_b128 v[28:31], v3 offset:5120
	ds_read_b128 v[32:35], v3 offset:6144
	ds_read_b128 v[36:39], v3 offset:7168
	ds_read_b128 v[40:43], v4
	ds_read_b128 v[44:47], v4 offset:1024
	ds_read_b128 v[48:51], v4 offset:2048
	ds_read_b128 v[52:55], v4 offset:3072
	ds_read_b128 v[56:59], v4 offset:4096
	ds_read_b128 v[60:63], v4 offset:5120
	ds_read_b128 v[64:67], v4 offset:6144
	ds_read_b128 v[68:71], v4 offset:7168
	v_pk_add_f32 v[206:207], v[206:207], v[210:211]
	v_pk_add_f32 v[204:205], v[204:205], v[208:209]
	v_pk_add_f32 v[198:199], v[198:199], v[202:203]
	v_pk_add_f32 v[196:197], v[196:197], v[200:201]
	v_pk_add_f32 v[198:199], v[206:207], v[198:199]
	v_pk_add_f32 v[196:197], v[204:205], v[196:197]
	v_pk_add_f32 v[200:201], v[222:223], v[236:237]
	v_pk_add_f32 v[202:203], v[220:221], v[234:235]
	v_pk_add_f32 v[204:205], v[214:215], v[218:219]
	v_pk_add_f32 v[206:207], v[212:213], v[216:217]
	v_pk_add_f32 v[200:201], v[200:201], v[204:205]
	v_pk_add_f32 v[202:203], v[202:203], v[206:207]
	v_pk_add_f32 v[198:199], v[198:199], v[200:201]
	v_pk_add_f32 v[196:197], v[196:197], v[202:203]
	s_nop 0
	v_pk_mov_b32 v[200:201], v[196:197], v[198:199] op_sel:[1,0]
	v_mov_b32_e32 v197, v199
	v_pk_add_f32 v[196:197], v[200:201], v[196:197]
	s_nop 0
	v_add_f32_e32 v196, v196, v197
	v_fmamk_f32 v196, v196, 0x3a000000, v225
	v_mul_f32_e32 v197, 0x4f800000, v196
	v_cmp_gt_f32_e32 vcc, 0xf800000, v196
	s_nop 1
	v_cndmask_b32_e32 v196, v196, v197, vcc
	v_sqrt_f32_e32 v197, v196
	s_nop 0
	v_add_u32_e32 v198, -1, v197
	v_fma_f32 v199, -v198, v197, v196
	v_cmp_ge_f32_e64 s[100:101], 0, v199
	v_add_u32_e32 v199, 1, v197
	s_nop 0
	v_cndmask_b32_e64 v198, v197, v198, s[100:101]
	v_fma_f32 v197, -v199, v197, v196
	v_cmp_lt_f32_e64 s[100:101], 0, v197
	s_nop 1
	v_cndmask_b32_e64 v197, v198, v199, s[100:101]
	v_mul_f32_e32 v198, 0x37800000, v197
	v_cndmask_b32_e32 v197, v197, v198, vcc
	v_cmp_class_f32_e32 vcc, v196, v226
	s_nop 1
	v_cndmask_b32_e32 v196, v197, v196, vcc
	v_div_scale_f32 v197, s[100:101], v196, v196, 1.0
	v_rcp_f32_e32 v198, v197
	s_nop 0
	v_fma_f32 v199, -v197, v198, 1.0
	v_fmac_f32_e32 v198, v199, v198
	v_div_scale_f32 v199, vcc, 1.0, v196, 1.0
	v_mul_f32_e32 v200, v199, v198
	v_fma_f32 v201, -v197, v200, v199
	v_fmac_f32_e32 v200, v201, v198
	v_fma_f32 v197, -v197, v200, v199
	v_div_fmas_f32 v197, v197, v198, v200
	v_div_fixup_f32 v196, v197, v196, 1.0
	s_waitcnt lgkmcnt(0)
	v_pk_add_f32 v[8:9], v[8:9], v[12:13]
	v_pk_add_f32 v[10:11], v[10:11], v[14:15]
	v_pk_add_f32 v[16:17], v[16:17], v[20:21]
	v_pk_add_f32 v[18:19], v[18:19], v[22:23]
	v_pk_add_f32 v[24:25], v[24:25], v[28:29]
	v_pk_add_f32 v[26:27], v[26:27], v[30:31]
	v_pk_add_f32 v[32:33], v[32:33], v[36:37]
	v_pk_add_f32 v[34:35], v[34:35], v[38:39]
	v_pk_add_f32 v[8:9], v[8:9], v[16:17]
	v_pk_add_f32 v[10:11], v[10:11], v[18:19]
	v_pk_add_f32 v[24:25], v[24:25], v[32:33]
	v_pk_add_f32 v[26:27], v[26:27], v[34:35]
	v_pk_add_f32 v[8:9], v[8:9], v[24:25]
	v_pk_add_f32 v[10:11], v[10:11], v[26:27]
	v_pk_add_f32 v[40:41], v[40:41], v[44:45]
	v_pk_add_f32 v[42:43], v[42:43], v[46:47]
	v_pk_add_f32 v[48:49], v[48:49], v[52:53]
	v_pk_add_f32 v[50:51], v[50:51], v[54:55]
	v_pk_add_f32 v[56:57], v[56:57], v[60:61]
	v_pk_add_f32 v[58:59], v[58:59], v[62:63]
	v_pk_add_f32 v[64:65], v[64:65], v[68:69]
	v_pk_add_f32 v[66:67], v[66:67], v[70:71]
	v_pk_add_f32 v[40:41], v[40:41], v[48:49]
	v_pk_add_f32 v[42:43], v[42:43], v[50:51]
	v_pk_add_f32 v[56:57], v[56:57], v[64:65]
	v_pk_add_f32 v[58:59], v[58:59], v[66:67]
	v_pk_add_f32 v[40:41], v[40:41], v[56:57]
	v_pk_add_f32 v[42:43], v[42:43], v[58:59]
	v_mul_f32_e32 v8, v8, v196
	v_mul_f32_e32 v9, v9, v196
	v_mul_f32_e32 v10, v10, v196
	v_mul_f32_e32 v11, v11, v196
	v_mul_f32_e32 v40, v40, v196
	v_mul_f32_e32 v41, v41, v196
	v_mul_f32_e32 v42, v42, v196
	v_mul_f32_e32 v43, v43, v196
	v_cvt_pk_bf16_f32 v8, v8, v9
	v_cvt_pk_bf16_f32 v9, v10, v11
	v_cvt_pk_bf16_f32 v40, v40, v41
	v_cvt_pk_bf16_f32 v41, v42, v43
	s_lshl_b32 s3, s3, 5
	v_add_u32_e32 v5, s3, v242
	global_store_dwordx2 v5, v[8:9], s[16:17]
	global_store_dwordx2 v242, v[40:41], s[16:17] offset:64
	s_load_dword s2, s[88:89], 0x148
	s_waitcnt lgkmcnt(0)
	s_add_i32 s2, s2, m0
	s_mov_b32 m0, s2
	s_barrier
	s_cmpk_lt_u32 s2, 0x100
	s_cbranch_scc1 .Lvres_chunk
